# v026 plus write-through (sc1) stores in the plain bf16 store epilogue (mixer-in and Q/K outputs)
# speedup vs baseline: 1.0077x; 1.0024x over previous
; DI unsigned pk2(float lo, float hi) { f32x2 v = {lo, hi}; return __builtin_bit_cast(unsigned, __builtin_convertvector(v, bf2_t)); }
;     DI void operator()(const f32x4 (&acc)[2][2][4][2], const Unit& u, int wr, int wc, int fr, int fq) const {
;     ...
; #pragma unroll
;         for (int ai = 0; ai < 2; ++ai)
; #pragma unroll
;             for (int m = 0; m < 4; ++m) {
;                 bf16_t* rowp = O + (size_t)(row0 + ai * HALF + m * 16) * ldc + col0;
; #pragma unroll
;                 for (int bj = 0; bj < 2; ++bj) {
;                     const f32x4 v0 = acc[ai][bj][m][0] * sv[bj][0], v1 = acc[ai][bj][m][1] * sv[bj][1];
;                     u32x4 w; w.x = pk2(v0[0], v0[1]); w.y = pk2(v0[2], v0[3]); w.z = pk2(v1[0], v1[1]); w.w = pk2(v1[2], v1[3]);
;                     *(u32x4*)(rowp + bj * HALF) = w;
;                 }
;             }
.LBB0_129:
	v_mul_lo_u32 v34, s49, v150
	v_mul_lo_u32 v41, s48, v154
	v_mad_u64_u32 v[32:33], s[20:21], s48, v150, 0
	v_ashrrev_i32_e32 v145, 31, v144
	v_add3_u32 v33, v33, v41, v34
	v_lshl_add_u64 v[32:33], v[32:33], 1, s[50:51]
	v_lshlrev_b64 v[34:35], 1, v[144:145]
	v_lshl_add_u64 v[32:33], v[32:33], 0, v[34:35]
	global_store_dwordx4 v[32:33], v[130:133], off sc1
	global_store_dwordx4 v[32:33], v[118:121], off offset:256 sc1
	v_mul_lo_u32 v42, s49, v153
	v_mad_u64_u32 v[32:33], s[20:21], s48, v153, 0
	v_add3_u32 v33, v33, v41, v42
	v_lshl_add_u64 v[32:33], v[32:33], 1, s[50:51]
	v_lshl_add_u64 v[32:33], v[32:33], 0, v[34:35]
	global_store_dwordx4 v[32:33], v[110:113], off sc1
	global_store_dwordx4 v[32:33], v[102:105], off offset:256 sc1
	v_mul_lo_u32 v42, s49, v152
	v_mad_u64_u32 v[32:33], s[20:21], s48, v152, 0
	v_add3_u32 v33, v33, v41, v42
	v_lshl_add_u64 v[32:33], v[32:33], 1, s[50:51]
	v_lshl_add_u64 v[32:33], v[32:33], 0, v[34:35]
	global_store_dwordx4 v[32:33], v[92:95], off sc1
	global_store_dwordx4 v[32:33], v[84:87], off offset:256 sc1
	v_mul_lo_u32 v42, s49, v151
	v_mad_u64_u32 v[32:33], s[20:21], s48, v151, 0
	v_add3_u32 v33, v33, v41, v42
	v_lshl_add_u64 v[32:33], v[32:33], 1, s[50:51]
	v_lshl_add_u64 v[32:33], v[32:33], 0, v[34:35]
	global_store_dwordx4 v[32:33], v[76:79], off sc1
	global_store_dwordx4 v[32:33], v[68:71], off offset:256 sc1
	v_ashrrev_i32_e32 v32, 31, v64
	v_mul_lo_u32 v41, s48, v32
	v_mul_lo_u32 v42, s49, v64
	v_mad_u64_u32 v[32:33], s[20:21], s48, v64, 0
	v_add3_u32 v33, v33, v41, v42
	v_lshl_add_u64 v[32:33], v[32:33], 1, s[50:51]
	v_lshl_add_u64 v[32:33], v[32:33], 0, v[34:35]
	global_store_dwordx4 v[32:33], v[60:63], off sc1
	global_store_dwordx4 v[32:33], v[52:55], off offset:256 sc1
	v_ashrrev_i32_e32 v32, 31, v48
	v_mul_lo_u32 v41, s48, v32
	v_mul_lo_u32 v42, s49, v48
	v_mad_u64_u32 v[32:33], s[20:21], s48, v48, 0
	v_add3_u32 v33, v33, v41, v42
	v_lshl_add_u64 v[32:33], v[32:33], 1, s[50:51]
	v_lshl_add_u64 v[32:33], v[32:33], 0, v[34:35]
	v_cvt_pk_bf16_f32 v20, v20, v21
	v_cvt_pk_bf16_f32 v21, v22, v23
	v_cvt_pk_bf16_f32 v22, v16, v17
	v_add_u32_e32 v16, 0xb0, v150
	global_store_dwordx4 v[32:33], v[44:47], off sc1
	global_store_dwordx4 v[32:33], v[36:39], off offset:256 sc1
	v_ashrrev_i32_e32 v32, 31, v40
	v_ashrrev_i32_e32 v17, 31, v16
	v_mul_lo_u32 v36, s48, v32
	v_mul_lo_u32 v37, s49, v40
	v_mad_u64_u32 v[32:33], s[20:21], s48, v40, 0
	v_cvt_pk_bf16_f32 v23, v18, v19
	v_mul_lo_u32 v18, s48, v17
	v_mul_lo_u32 v19, s49, v16
	v_mad_u64_u32 v[16:17], s[20:21], s48, v16, 0
	v_add3_u32 v33, v33, v36, v37
	v_add3_u32 v17, v17, v18, v19
	v_lshl_add_u64 v[32:33], v[32:33], 1, s[50:51]
	v_lshl_add_u64 v[16:17], v[16:17], 1, s[50:51]
	v_lshl_add_u64 v[32:33], v[32:33], 0, v[34:35]
	v_cvt_pk_bf16_f32 v28, v28, v29
	v_cvt_pk_bf16_f32 v29, v30, v31
	v_cvt_pk_bf16_f32 v30, v24, v25
	v_cvt_pk_bf16_f32 v31, v26, v27
	v_lshl_add_u64 v[16:17], v[16:17], 0, v[34:35]
	v_cvt_pk_bf16_f32 v12, v12, v13
	v_cvt_pk_bf16_f32 v13, v14, v15
	v_cvt_pk_bf16_f32 v14, v8, v9
	v_cvt_pk_bf16_f32 v15, v10, v11
	v_cvt_pk_bf16_f32 v4, v4, v5
	v_cvt_pk_bf16_f32 v5, v6, v7
	v_cvt_pk_bf16_f32 v6, v0, v1
	v_cvt_pk_bf16_f32 v7, v2, v3
	global_store_dwordx4 v[32:33], v[28:31], off sc1
	global_store_dwordx4 v[32:33], v[20:23], off offset:256 sc1
	global_store_dwordx4 v[16:17], v[12:15], off sc1
	global_store_dwordx4 v[16:17], v[4:7], off offset:256 sc1
	s_and_b64 vcc, exec, s[40:41]
	s_mov_b64 s[20:21], -1
	s_cbranch_vccnz .LBB0_113
